# v16 + P7 two-row-pair pipelining + P2 conv-before-sample order on odd workgroups
# speedup vs baseline: 1.0415x; 1.0065x over previous
; #define PG8_LAS __attribute__((address_space(3)))
; #define XLAS __attribute__((address_space(3)))
; __global__ void __launch_bounds__(512, 2) hymba_fwd(Params p) {
;     extern __shared__ __attribute__((aligned(16))) unsigned char lds[];
;     cg::grid_group grid = cg::this_grid();
;     unsigned char* ws = p.ws;
;     PG8_LAS unsigned char* glds = (PG8_LAS unsigned char*)lds;
;     const int G = gridDim.x, bx = blockIdx.x;
;     if (p.ws == nullptr) grid.sync();
;     volatile XLAS unsigned* xst = (volatile XLAS unsigned*)(glds + LDS_MAIN);
;     if (threadIdx.x < 4) xst[threadIdx.x] = 0u;
;     __syncthreads();
;     const XcdBarrier gbar = xcd_barrier_post((unsigned*)(ws + WS_BAR), xst);
_Z9hymba_fwd6Params:
	s_mov_b32 s98, 0
	s_load_dwordx4 s[64:67], s[0:1], 0xc0
	s_add_u32 s6, s0, 0xc8
	s_addc_u32 s7, s1, 0
	s_mov_b64 s[4:5], 0
	s_waitcnt lgkmcnt(0)
	s_cmp_eq_u64 s[64:65], 0
	s_cbranch_scc1 .LBB0_2
	v_and_b32_e32 v176, 0x3ff, v0
	s_load_dword s89, s[0:1], 0xd0
	s_andn2_b64 vcc, exec, s[4:5]
	s_cbranch_vccz .LBB0_3
	s_branch .LBB0_14

; __device__ __forceinline__ float bf2f(bf16_t b) { return __uint_as_float(((unsigned)b) << 16); }
; __device__ __forceinline__ void hgrn_sample_pair(const Params& p, float* lds, int unit) {
;     int tid = threadIdx.x; asm volatile("" : "+v"(tid));
;     const int half = tid >> 8, v = tid & 127, kg = (tid >> 7) & 1, lane = tid & 63, wq = (tid >> 6) & 3;
;     unsigned char* ws = p.ws;
;     const bf16_t* Q = (const bf16_t*)(ws + WS_Q); const bf16_t* Kk = (const bf16_t*)(ws + WS_K); const bf16_t* V = (const bf16_t*)(ws + WS_V); const bf16_t* Gt = (const bf16_t*)(ws + WS_G);
;     const float* LOGF = (const float*)(ws + WS_LOGF); bf16_t* CAT = (bf16_t*)(ws + WS_CAT);
;     const int n = unit >> 2, h = unit & 3, rowbase = MP + n * DS;
;     float* sq = lds + half * 3072; float* sk = sq + 512; float* sf = sq + 1024; float* sv = sq + 1536; float* po = sq + 2048;
;     float S[64]; float gn0 = 0.f, gn1 = 0.f, gt0 = 0.f, gt1 = 0.f;
;     if (unit >= 0) {
;         { const size_t g = (size_t)(rowbase + wq) * 512 + h * 128; gn0 = p.in[I_HON][lane]; gn1 = p.in[I_HON][lane + 64]; gt0 = bf2f(Gt[g + lane]); gt1 = bf2f(Gt[g + lane + 64]); }
;         const float* s0 = p.in[I_SH] + ((size_t)(n * HEADS + h) * DK) * DV + (size_t)(64 * kg) * DV + v;
; #pragma unroll
;         for (int k = 0; k < 64; ++k) S[k] = __builtin_nontemporal_load(s0 + (size_t)k * DV);
; #pragma unroll
;         for (int i = 0; i < 2; ++i) { const int idx = (tid & 255) + 256 * i, t = idx >> 7, c = idx & 127; const size_t g = (size_t)(rowbase + t) * 512 + h * 128 + c;
;             sq[idx] = bf2f(Q[g]); sk[idx] = bf2f(Kk[g]); sf[idx] = __builtin_amdgcn_exp2f(LOGF[g]); sv[idx] = bf2f(V[g]); }
; __global__ void __launch_bounds__(512, 2) hymba_fwd(Params p) {
;     ...
;         for (int u = G - 1 - bx; u < DB * HEADS / 2; u += G) hgrn_sample_pair(p, (float*)lds, 2 * u + (threadIdx.x >> 8));
;         for (int u = CONV_MOVED + bx; u < NB * (SEQ / 16) / 2; u += G) conv_pair<16>(p, lds, false, 2 * u + (threadIdx.x >> 8));
.LBB0_324:
	s_not_b32 s0, s2
	s_add_i32 s0, s66, s0
	v_lshrrev_b32_e32 v96, 8, v176
	s_bitcmp1_b32 s2, 0
	s_cbranch_scc0 .Lp2_samp
	s_cmp_eq_u32 s98, 0
	s_cbranch_scc0 .Lp2_samp
	s_mov_b32 s98, 1
	s_branch .LBB0_333
.Lp2_samp:
	s_cmpk_gt_i32 s0, 0xff
	s_cbranch_scc1 .LBB0_333
	v_readlane_b32 s8, v247, 16
	v_readlane_b32 s12, v247, 20
	v_readlane_b32 s13, v247, 21
	v_readlane_b32 s14, v247, 22
	v_readlane_b32 s15, v247, 23
	v_readlane_b32 s20, v247, 28
	v_readlane_b32 s21, v247, 29
	s_add_u32 s6, s64, 0x54f5e00
	v_readlane_b32 s22, v247, 30
	v_readlane_b32 s23, v247, 31
	s_mov_b64 s[12:13], s[20:21]
	s_addc_u32 s7, s65, 0
	s_mov_b64 s[14:15], s[22:23]
	v_readlane_b32 s9, v247, 17
	s_add_u32 s8, s14, 0x4478000
	s_addc_u32 s9, s15, 0
	s_lshl_b32 s1, s66, 1
	v_add_u32_e32 v0, s1, v96
	s_lshl_b32 s3, s2, 1
	v_readlane_b32 s16, v247, 24
	v_readlane_b32 s17, v247, 25
	v_readlane_b32 s18, v247, 26
	v_readlane_b32 s19, v247, 27
	v_subrev_u32_e32 v0, s3, v0
	v_add_u32_e32 v0, -2, v0
	s_movk_i32 s3, 0x4000
	s_movk_i32 s12, 0x3000
	v_mov_b32_e32 v3, 0
	s_movk_i32 s13, 0x1000
	s_movk_i32 s14, 0x2000
	s_movk_i32 s15, 0x5000
	s_movk_i32 s16, 0x6000
	s_movk_i32 s17, 0x7000
	v_mov_b32_e32 v14, 0x358637bd
	s_mov_b32 s18, 0x800000
	s_mov_b32 s19, s0
	v_readlane_b32 s10, v247, 18
	v_readlane_b32 s11, v247, 19
	s_branch .LBB0_327

; __global__ void __launch_bounds__(512, 2) hymba_fwd(Params p) {
;     ...
;         for (int u = G - 1 - bx; u < DB * HEADS / 2; u += G) hgrn_sample_pair(p, (float*)lds, 2 * u + (threadIdx.x >> 8));
;         for (int u = CONV_MOVED + bx; u < NB * (SEQ / 16) / 2; u += G) conv_pair<16>(p, lds, false, 2 * u + (threadIdx.x >> 8));
;         { const int ib = G - 1 - bx, nb2 = G < 32 ? G : 32;
;           if (ib < nb2) for (int u = ib; u < DB / 2; u += nb2) conv_pair<DS>(p, lds, true, 2 * u + (threadIdx.x >> 8)); }
.LBB0_333:
	s_cmp_eq_u32 s98, 2
	s_cbranch_scc0 .Lp2_conv
	s_mov_b32 s98, 0
	s_cmpk_lt_i32 s2, 0x100
	s_cselect_b64 s[28:29], -1, 0
	s_branch .LBB0_400

; __global__ void __launch_bounds__(512, 2) hymba_fwd(Params p) {
;     ...
;         for (int u = G - 1 - bx; u < DB * HEADS / 2; u += G) hgrn_sample_pair(p, (float*)lds, 2 * u + (threadIdx.x >> 8));
;         for (int u = CONV_MOVED + bx; u < NB * (SEQ / 16) / 2; u += G) conv_pair<16>(p, lds, false, 2 * u + (threadIdx.x >> 8));
;         { const int ib = G - 1 - bx, nb2 = G < 32 ? G : 32;
;           if (ib < nb2) for (int u = ib; u < DB / 2; u += nb2) conv_pair<DS>(p, lds, true, 2 * u + (threadIdx.x >> 8)); }
.LBB0_400:
	s_cmp_eq_u32 s98, 1
	s_cbranch_scc0 .Lp2_sconv
	s_mov_b32 s98, 2
	s_branch .Lp2_samp

; __device__ __forceinline__ f32x4 unpack4(const u32x2& w) { f32x4 a; a[0] = __uint_as_float(w.x << 16); a[1] = __uint_as_float(w.x & 0xffff0000u); a[2] = __uint_as_float(w.y << 16); a[3] = __uint_as_float(w.y & 0xffff0000u); return a; }
; __global__ void __launch_bounds__(512, 2) hymba_fwd(Params p) {
;     ...
;         const int lane = threadIdx.x & 63, gw = bx * 8 + (threadIdx.x >> 6), NGW = G * 8;
;         const f32x4* gp = (const f32x4*)p.in[I_NFIN] + lane; f32x4 gv[4];
; #pragma unroll
;         for (int j = 0; j < 4; ++j) gv[j] = gp[64 * j];
;         const bf16_t* H3 = (const bf16_t*)(ws + WS_H3); const float* ss3 = (const float*)(ws + WS_SS3);
;         for (int m0 = 2 * gw; m0 < MT; m0 += 2 * NGW) { const int m1 = m0 + 1;
;             const float r0 = rsqrtf(ss3[m0] * (1.0f / DM) + EPS), r1 = rsqrtf(ss3[m1] * (1.0f / DM) + EPS);
;             u32x2 h0[4], h1[4];
; #pragma unroll
;             for (int j = 0; j < 4; ++j) { h0[j] = __builtin_nontemporal_load((const u32x2*)(H3 + (size_t)m0 * DM) + lane + 64 * j); h1[j] = __builtin_nontemporal_load((const u32x2*)(H3 + (size_t)m1 * DM) + lane + 64 * j); }
; #pragma unroll
;             for (int j = 0; j < 4; ++j) { __builtin_nontemporal_store(unpack4(h0[j]) * r0 * gv[j], (f32x4*)(p.out + (size_t)m0 * DM) + lane + 64 * j); __builtin_nontemporal_store(unpack4(h1[j]) * r1 * gv[j], (f32x4*)(p.out + (size_t)m1 * DM) + lane + 64 * j); } }
.LBB0_955:
	v_lshl_add_u64 v[26:27], s[64:65], 0, v[18:19]
	global_load_dwordx2 v[26:27], v[26:27], off
	v_lshl_add_u64 v[28:29], s[64:65], 0, v[20:21]
	v_add_co_u32_e32 v30, vcc, s13, v28
	v_add_u32_e32 v16, s2, v16
	s_nop 0
	v_addc_co_u32_e32 v31, vcc, 0, v29, vcc
	v_add_co_u32_e32 v28, vcc, s14, v28
	v_lshl_add_u64 v[18:19], v[18:19], 0, s[4:5]
	s_nop 0
	v_addc_co_u32_e32 v29, vcc, 0, v29, vcc
	global_load_dwordx2 v[32:33], v[30:31], off offset:3584 nt
	global_load_dwordx2 v[34:35], v[28:29], off offset:1536 nt
	global_load_dwordx2 v[36:37], v[28:29], off nt
	global_load_dwordx2 v[38:39], v[28:29], off offset:2048 nt
	global_load_dwordx2 v[40:41], v[28:29], off offset:512 nt
	global_load_dwordx2 v[42:43], v[28:29], off offset:2560 nt
	global_load_dwordx2 v[44:45], v[28:29], off offset:1024 nt
	global_load_dwordx2 v[46:47], v[28:29], off offset:3072 nt
	v_cmp_lt_i32_e32 vcc, s15, v16
	s_or_b64 s[10:11], vcc, s[10:11]
	v_lshl_add_u64 v[20:21], v[20:21], 0, s[6:7]
	s_mov_b64 s[98:99], exec
	s_andn2_b64 exec, exec, s[10:11]
	s_cbranch_execz .Lp7_single
	v_lshl_add_u64 v[70:71], s[64:65], 0, v[18:19]
	global_load_dwordx2 v[70:71], v[70:71], off
	v_lshl_add_u64 v[88:89], s[64:65], 0, v[20:21]
	v_add_co_u32_e32 v90, vcc, s13, v88
	v_add_u32_e32 v16, s2, v16
	s_nop 0
	v_addc_co_u32_e32 v91, vcc, 0, v89, vcc
	v_add_co_u32_e32 v88, vcc, s14, v88
	v_lshl_add_u64 v[18:19], v[18:19], 0, s[4:5]
	s_nop 0
	v_addc_co_u32_e32 v89, vcc, 0, v89, vcc
	global_load_dwordx2 v[72:73], v[90:91], off offset:3584 nt
	global_load_dwordx2 v[74:75], v[88:89], off offset:1536 nt
	global_load_dwordx2 v[76:77], v[88:89], off nt
	global_load_dwordx2 v[78:79], v[88:89], off offset:2048 nt
	global_load_dwordx2 v[80:81], v[88:89], off offset:512 nt
	global_load_dwordx2 v[82:83], v[88:89], off offset:2560 nt
	global_load_dwordx2 v[84:85], v[88:89], off offset:1024 nt
	global_load_dwordx2 v[86:87], v[88:89], off offset:3072 nt
	v_cmp_lt_i32_e32 vcc, s15, v16
	s_or_b64 s[10:11], vcc, s[10:11]
	v_lshl_add_u64 v[20:21], v[20:21], 0, s[6:7]
	s_mov_b64 s[100:101], exec
	s_mov_b64 exec, s[98:99]
	s_waitcnt vmcnt(17)
	v_pk_fma_f32 v[26:27], v[26:27], s[12:13], v[24:25] op_sel_hi:[1,0,0]
	s_nop 0
	v_mul_f32_e32 v17, 0x4b800000, v26
	v_cmp_gt_f32_e64 s[0:1], s3, v26
	v_mul_f32_e32 v25, 0x4b800000, v27
	v_cmp_gt_f32_e32 vcc, s3, v27
	v_cndmask_b32_e64 v17, v26, v17, s[0:1]
	v_rsq_f32_e32 v17, v17
	v_cndmask_b32_e32 v25, v27, v25, vcc
	v_rsq_f32_e32 v25, v25
	s_waitcnt vmcnt(16)
	v_lshlrev_b32_e32 v28, 16, v32
	v_mul_f32_e32 v26, 0x45800000, v17
	v_and_b32_e32 v29, 0xffff0000, v32
	v_lshlrev_b32_e32 v30, 16, v33
	v_and_b32_e32 v31, 0xffff0000, v33
	v_mul_f32_e32 v27, 0x45800000, v25
	v_cndmask_b32_e64 v26, v17, v26, s[0:1]
	s_waitcnt vmcnt(15)
	v_lshlrev_b32_e32 v32, 16, v34
	v_and_b32_e32 v33, 0xffff0000, v34
	v_lshlrev_b32_e32 v34, 16, v35
	v_and_b32_e32 v35, 0xffff0000, v35
	s_waitcnt vmcnt(14)
	v_lshlrev_b32_e32 v48, 16, v36
	v_and_b32_e32 v49, 0xffff0000, v36
	v_lshlrev_b32_e32 v36, 16, v37
	v_and_b32_e32 v37, 0xffff0000, v37
	s_waitcnt vmcnt(13)
	v_lshlrev_b32_e32 v50, 16, v38
	v_and_b32_e32 v51, 0xffff0000, v38
	v_lshlrev_b32_e32 v38, 16, v39
	v_and_b32_e32 v39, 0xffff0000, v39
	s_waitcnt vmcnt(12)
	v_lshlrev_b32_e32 v52, 16, v40
	v_and_b32_e32 v53, 0xffff0000, v40
	v_lshlrev_b32_e32 v40, 16, v41
	v_and_b32_e32 v41, 0xffff0000, v41
	s_waitcnt vmcnt(11)
	v_lshlrev_b32_e32 v54, 16, v42
	v_and_b32_e32 v55, 0xffff0000, v42
	v_lshlrev_b32_e32 v42, 16, v43
	v_and_b32_e32 v43, 0xffff0000, v43
	s_waitcnt vmcnt(10)
	v_lshlrev_b32_e32 v56, 16, v44
	v_and_b32_e32 v57, 0xffff0000, v44
	v_lshlrev_b32_e32 v44, 16, v45
	v_and_b32_e32 v45, 0xffff0000, v45
	s_waitcnt vmcnt(9)
	v_lshlrev_b32_e32 v58, 16, v46
	v_and_b32_e32 v59, 0xffff0000, v46
	v_lshlrev_b32_e32 v46, 16, v47
	v_and_b32_e32 v47, 0xffff0000, v47
	v_cndmask_b32_e32 v60, v25, v27, vcc
	v_pk_mul_f32 v[62:63], v[26:27], v[28:29] op_sel_hi:[0,1]
	v_pk_mul_f32 v[28:29], v[26:27], v[30:31] op_sel_hi:[0,1]
	v_pk_mul_f32 v[30:31], v[60:61], v[32:33] op_sel_hi:[0,1]
	v_pk_mul_f32 v[32:33], v[60:61], v[34:35] op_sel_hi:[0,1]
	v_pk_mul_f32 v[34:35], v[26:27], v[48:49] op_sel_hi:[0,1]
	v_pk_mul_f32 v[36:37], v[26:27], v[36:37] op_sel_hi:[0,1]
	v_pk_mul_f32 v[48:49], v[60:61], v[50:51] op_sel_hi:[0,1]
	v_pk_mul_f32 v[38:39], v[60:61], v[38:39] op_sel_hi:[0,1]
	v_pk_mul_f32 v[50:51], v[26:27], v[52:53] op_sel_hi:[0,1]
	v_pk_mul_f32 v[52:53], v[26:27], v[40:41] op_sel_hi:[0,1]
	v_pk_mul_f32 v[54:55], v[60:61], v[54:55] op_sel_hi:[0,1]
	v_pk_mul_f32 v[64:65], v[60:61], v[42:43] op_sel_hi:[0,1]
	v_pk_mul_f32 v[56:57], v[26:27], v[56:57] op_sel_hi:[0,1]
	v_pk_mul_f32 v[66:67], v[26:27], v[44:45] op_sel_hi:[0,1]
	v_pk_mul_f32 v[58:59], v[60:61], v[58:59] op_sel_hi:[0,1]
	v_pk_mul_f32 v[60:61], v[60:61], v[46:47] op_sel_hi:[0,1]
	v_pk_mul_f32 v[28:29], v[2:3], v[28:29]
	v_pk_mul_f32 v[26:27], v[0:1], v[62:63]
	v_pk_mul_f32 v[32:33], v[2:3], v[32:33]
	v_pk_mul_f32 v[30:31], v[0:1], v[30:31]
	v_pk_mul_f32 v[36:37], v[6:7], v[36:37]
	v_pk_mul_f32 v[34:35], v[4:5], v[34:35]
	v_pk_mul_f32 v[40:41], v[6:7], v[38:39]
	v_pk_mul_f32 v[38:39], v[4:5], v[48:49]
	v_pk_mul_f32 v[44:45], v[10:11], v[52:53]
	v_pk_mul_f32 v[42:43], v[8:9], v[50:51]
	v_pk_mul_f32 v[48:49], v[10:11], v[64:65]
	v_pk_mul_f32 v[46:47], v[8:9], v[54:55]
	v_pk_mul_f32 v[52:53], v[14:15], v[66:67]
	v_pk_mul_f32 v[50:51], v[12:13], v[56:57]
	v_pk_mul_f32 v[56:57], v[14:15], v[60:61]
	v_pk_mul_f32 v[54:55], v[12:13], v[58:59]
	global_store_dwordx4 v[22:23], v[26:29], off offset:-4096 nt
	global_store_dwordx4 v[22:23], v[30:33], off nt
	global_store_dwordx4 v[22:23], v[34:37], off offset:-3072 nt
	global_store_dwordx4 v[22:23], v[38:41], off offset:1024 nt
	global_store_dwordx4 v[22:23], v[42:45], off offset:-2048 nt
	global_store_dwordx4 v[22:23], v[46:49], off offset:2048 nt
	global_store_dwordx4 v[22:23], v[50:53], off offset:-1024 nt
	global_store_dwordx4 v[22:23], v[54:57], off offset:3072 nt
	v_lshl_add_u64 v[22:23], v[22:23], 0, s[8:9]
	s_mov_b64 exec, s[100:101]
	s_waitcnt vmcnt(8)
; __device__ __forceinline__ f32x4 unpack4(const u32x2& w) { f32x4 a; a[0] = __uint_as_float(w.x << 16); a[1] = __uint_as_float(w.x & 0xffff0000u); a[2] = __uint_as_float(w.y << 16); a[3] = __uint_as_float(w.y & 0xffff0000u); return a; }
; __global__ void __launch_bounds__(512, 2) hymba_fwd(Params p) {
;     ...
;         for (int m0 = 2 * gw; m0 < MT; m0 += 2 * NGW) { const int m1 = m0 + 1;
;             const float r0 = rsqrtf(ss3[m0] * (1.0f / DM) + EPS), r1 = rsqrtf(ss3[m1] * (1.0f / DM) + EPS);
;             u32x2 h0[4], h1[4];
; #pragma unroll
;             for (int j = 0; j < 4; ++j) { h0[j] = __builtin_nontemporal_load((const u32x2*)(H3 + (size_t)m0 * DM) + lane + 64 * j); h1[j] = __builtin_nontemporal_load((const u32x2*)(H3 + (size_t)m1 * DM) + lane + 64 * j); }
; #pragma unroll
;             for (int j = 0; j < 4; ++j) { __builtin_nontemporal_store(unpack4(h0[j]) * r0 * gv[j], (f32x4*)(p.out + (size_t)m0 * DM) + lane + 64 * j); __builtin_nontemporal_store(unpack4(h1[j]) * r1 * gv[j], (f32x4*)(p.out + (size_t)m1 * DM) + lane + 64 * j); } }
	v_mov_b32_e32 v26, v70
	v_mov_b32_e32 v27, v71
	v_mov_b32_e32 v32, v72
	v_mov_b32_e32 v33, v73
	v_mov_b32_e32 v34, v74
	v_mov_b32_e32 v35, v75
	v_mov_b32_e32 v36, v76
	v_mov_b32_e32 v37, v77
	v_mov_b32_e32 v38, v78
	v_mov_b32_e32 v39, v79
	v_mov_b32_e32 v40, v80
	v_mov_b32_e32 v41, v81
	v_mov_b32_e32 v42, v82
	v_mov_b32_e32 v43, v83
	v_mov_b32_e32 v44, v84
	v_mov_b32_e32 v45, v85
	v_mov_b32_e32 v46, v86
	v_mov_b32_e32 v47, v87
	v_pk_fma_f32 v[26:27], v[26:27], s[12:13], v[24:25] op_sel_hi:[1,0,0]
	s_nop 0
	v_mul_f32_e32 v17, 0x4b800000, v26
	v_cmp_gt_f32_e64 s[0:1], s3, v26
	v_mul_f32_e32 v25, 0x4b800000, v27
	v_cmp_gt_f32_e32 vcc, s3, v27
	v_cndmask_b32_e64 v17, v26, v17, s[0:1]
	v_rsq_f32_e32 v17, v17
	v_cndmask_b32_e32 v25, v27, v25, vcc
	v_rsq_f32_e32 v25, v25
	v_lshlrev_b32_e32 v28, 16, v32
	v_mul_f32_e32 v26, 0x45800000, v17
	v_and_b32_e32 v29, 0xffff0000, v32
	v_lshlrev_b32_e32 v30, 16, v33
	v_and_b32_e32 v31, 0xffff0000, v33
	v_mul_f32_e32 v27, 0x45800000, v25
	v_cndmask_b32_e64 v26, v17, v26, s[0:1]
	v_lshlrev_b32_e32 v32, 16, v34
	v_and_b32_e32 v33, 0xffff0000, v34
	v_lshlrev_b32_e32 v34, 16, v35
	v_and_b32_e32 v35, 0xffff0000, v35
	v_lshlrev_b32_e32 v48, 16, v36
	v_and_b32_e32 v49, 0xffff0000, v36
	v_lshlrev_b32_e32 v36, 16, v37
	v_and_b32_e32 v37, 0xffff0000, v37
	v_lshlrev_b32_e32 v50, 16, v38
	v_and_b32_e32 v51, 0xffff0000, v38
	v_lshlrev_b32_e32 v38, 16, v39
	v_and_b32_e32 v39, 0xffff0000, v39
	v_lshlrev_b32_e32 v52, 16, v40
	v_and_b32_e32 v53, 0xffff0000, v40
	v_lshlrev_b32_e32 v40, 16, v41
	v_and_b32_e32 v41, 0xffff0000, v41
	v_lshlrev_b32_e32 v54, 16, v42
	v_and_b32_e32 v55, 0xffff0000, v42
	v_lshlrev_b32_e32 v42, 16, v43
	v_and_b32_e32 v43, 0xffff0000, v43
	v_lshlrev_b32_e32 v56, 16, v44
	v_and_b32_e32 v57, 0xffff0000, v44
	v_lshlrev_b32_e32 v44, 16, v45
	v_and_b32_e32 v45, 0xffff0000, v45
	v_lshlrev_b32_e32 v58, 16, v46
	v_and_b32_e32 v59, 0xffff0000, v46
	v_lshlrev_b32_e32 v46, 16, v47
	v_and_b32_e32 v47, 0xffff0000, v47
	v_cndmask_b32_e32 v60, v25, v27, vcc
	v_pk_mul_f32 v[62:63], v[26:27], v[28:29] op_sel_hi:[0,1]
	v_pk_mul_f32 v[28:29], v[26:27], v[30:31] op_sel_hi:[0,1]
	v_pk_mul_f32 v[30:31], v[60:61], v[32:33] op_sel_hi:[0,1]
	v_pk_mul_f32 v[32:33], v[60:61], v[34:35] op_sel_hi:[0,1]
	v_pk_mul_f32 v[34:35], v[26:27], v[48:49] op_sel_hi:[0,1]
	v_pk_mul_f32 v[36:37], v[26:27], v[36:37] op_sel_hi:[0,1]
	v_pk_mul_f32 v[48:49], v[60:61], v[50:51] op_sel_hi:[0,1]
	v_pk_mul_f32 v[38:39], v[60:61], v[38:39] op_sel_hi:[0,1]
	v_pk_mul_f32 v[50:51], v[26:27], v[52:53] op_sel_hi:[0,1]
	v_pk_mul_f32 v[52:53], v[26:27], v[40:41] op_sel_hi:[0,1]
	v_pk_mul_f32 v[54:55], v[60:61], v[54:55] op_sel_hi:[0,1]
	v_pk_mul_f32 v[64:65], v[60:61], v[42:43] op_sel_hi:[0,1]
	v_pk_mul_f32 v[56:57], v[26:27], v[56:57] op_sel_hi:[0,1]
	v_pk_mul_f32 v[66:67], v[26:27], v[44:45] op_sel_hi:[0,1]
	v_pk_mul_f32 v[58:59], v[60:61], v[58:59] op_sel_hi:[0,1]
	v_pk_mul_f32 v[60:61], v[60:61], v[46:47] op_sel_hi:[0,1]
	v_pk_mul_f32 v[28:29], v[2:3], v[28:29]
	v_pk_mul_f32 v[26:27], v[0:1], v[62:63]
	v_pk_mul_f32 v[32:33], v[2:3], v[32:33]
	v_pk_mul_f32 v[30:31], v[0:1], v[30:31]
	v_pk_mul_f32 v[36:37], v[6:7], v[36:37]
	v_pk_mul_f32 v[34:35], v[4:5], v[34:35]
	v_pk_mul_f32 v[40:41], v[6:7], v[38:39]
	v_pk_mul_f32 v[38:39], v[4:5], v[48:49]
	v_pk_mul_f32 v[44:45], v[10:11], v[52:53]
	v_pk_mul_f32 v[42:43], v[8:9], v[50:51]
	v_pk_mul_f32 v[48:49], v[10:11], v[64:65]
	v_pk_mul_f32 v[46:47], v[8:9], v[54:55]
	v_pk_mul_f32 v[52:53], v[14:15], v[66:67]
	v_pk_mul_f32 v[50:51], v[12:13], v[56:57]
	v_pk_mul_f32 v[56:57], v[14:15], v[60:61]
	v_pk_mul_f32 v[54:55], v[12:13], v[58:59]
	global_store_dwordx4 v[22:23], v[26:29], off offset:-4096 nt
	global_store_dwordx4 v[22:23], v[30:33], off nt
	global_store_dwordx4 v[22:23], v[34:37], off offset:-3072 nt
	global_store_dwordx4 v[22:23], v[38:41], off offset:1024 nt
	global_store_dwordx4 v[22:23], v[42:45], off offset:-2048 nt
	global_store_dwordx4 v[22:23], v[46:49], off offset:2048 nt
	global_store_dwordx4 v[22:23], v[50:53], off offset:-1024 nt
	global_store_dwordx4 v[22:23], v[54:57], off offset:3072 nt
	v_lshl_add_u64 v[22:23], v[22:23], 0, s[8:9]
	s_andn2_b64 exec, exec, s[10:11]
	s_cbranch_execnz .LBB0_955
	s_branch .LBB0_956
; __device__ __forceinline__ f32x4 unpack4(const u32x2& w) { f32x4 a; a[0] = __uint_as_float(w.x << 16); a[1] = __uint_as_float(w.x & 0xffff0000u); a[2] = __uint_as_float(w.y << 16); a[3] = __uint_as_float(w.y & 0xffff0000u); return a; }
; __global__ void __launch_bounds__(512, 2) hymba_fwd(Params p) {
;     ...
;         for (int m0 = 2 * gw; m0 < MT; m0 += 2 * NGW) { const int m1 = m0 + 1;
;             const float r0 = rsqrtf(ss3[m0] * (1.0f / DM) + EPS), r1 = rsqrtf(ss3[m1] * (1.0f / DM) + EPS);
;             u32x2 h0[4], h1[4];
; #pragma unroll
;             for (int j = 0; j < 4; ++j) { h0[j] = __builtin_nontemporal_load((const u32x2*)(H3 + (size_t)m0 * DM) + lane + 64 * j); h1[j] = __builtin_nontemporal_load((const u32x2*)(H3 + (size_t)m1 * DM) + lane + 64 * j); }
; #pragma unroll
;             for (int j = 0; j < 4; ++j) { __builtin_nontemporal_store(unpack4(h0[j]) * r0 * gv[j], (f32x4*)(p.out + (size_t)m0 * DM) + lane + 64 * j); __builtin_nontemporal_store(unpack4(h1[j]) * r1 * gv[j], (f32x4*)(p.out + (size_t)m1 * DM) + lane + 64 * j); } }
.Lp7_single:
	s_mov_b64 exec, s[98:99]
	s_waitcnt vmcnt(8)
	v_pk_fma_f32 v[26:27], v[26:27], s[12:13], v[24:25] op_sel_hi:[1,0,0]
	s_nop 0
	v_mul_f32_e32 v17, 0x4b800000, v26
	v_cmp_gt_f32_e64 s[0:1], s3, v26
	v_mul_f32_e32 v25, 0x4b800000, v27
	v_cmp_gt_f32_e32 vcc, s3, v27
	v_cndmask_b32_e64 v17, v26, v17, s[0:1]
	v_rsq_f32_e32 v17, v17
	v_cndmask_b32_e32 v25, v27, v25, vcc
	v_rsq_f32_e32 v25, v25
	s_waitcnt vmcnt(7)
	v_lshlrev_b32_e32 v28, 16, v32
	v_mul_f32_e32 v26, 0x45800000, v17
	v_and_b32_e32 v29, 0xffff0000, v32
	v_lshlrev_b32_e32 v30, 16, v33
	v_and_b32_e32 v31, 0xffff0000, v33
	v_mul_f32_e32 v27, 0x45800000, v25
	v_cndmask_b32_e64 v26, v17, v26, s[0:1]
	s_waitcnt vmcnt(6)
	v_lshlrev_b32_e32 v32, 16, v34
	v_and_b32_e32 v33, 0xffff0000, v34
	v_lshlrev_b32_e32 v34, 16, v35
	v_and_b32_e32 v35, 0xffff0000, v35
	s_waitcnt vmcnt(5)
	v_lshlrev_b32_e32 v48, 16, v36
	v_and_b32_e32 v49, 0xffff0000, v36
	v_lshlrev_b32_e32 v36, 16, v37
	v_and_b32_e32 v37, 0xffff0000, v37
	s_waitcnt vmcnt(4)
	v_lshlrev_b32_e32 v50, 16, v38
	v_and_b32_e32 v51, 0xffff0000, v38
	v_lshlrev_b32_e32 v38, 16, v39
	v_and_b32_e32 v39, 0xffff0000, v39
	s_waitcnt vmcnt(3)
	v_lshlrev_b32_e32 v52, 16, v40
	v_and_b32_e32 v53, 0xffff0000, v40
	v_lshlrev_b32_e32 v40, 16, v41
	v_and_b32_e32 v41, 0xffff0000, v41
	s_waitcnt vmcnt(2)
	v_lshlrev_b32_e32 v54, 16, v42
	v_and_b32_e32 v55, 0xffff0000, v42
	v_lshlrev_b32_e32 v42, 16, v43
	v_and_b32_e32 v43, 0xffff0000, v43
	s_waitcnt vmcnt(1)
	v_lshlrev_b32_e32 v56, 16, v44
	v_and_b32_e32 v57, 0xffff0000, v44
	v_lshlrev_b32_e32 v44, 16, v45
	v_and_b32_e32 v45, 0xffff0000, v45
	s_waitcnt vmcnt(0)
	v_lshlrev_b32_e32 v58, 16, v46
	v_and_b32_e32 v59, 0xffff0000, v46
	v_lshlrev_b32_e32 v46, 16, v47
	v_and_b32_e32 v47, 0xffff0000, v47
	v_cndmask_b32_e32 v60, v25, v27, vcc
	v_pk_mul_f32 v[62:63], v[26:27], v[28:29] op_sel_hi:[0,1]
	v_pk_mul_f32 v[28:29], v[26:27], v[30:31] op_sel_hi:[0,1]
	v_pk_mul_f32 v[30:31], v[60:61], v[32:33] op_sel_hi:[0,1]
	v_pk_mul_f32 v[32:33], v[60:61], v[34:35] op_sel_hi:[0,1]
	v_pk_mul_f32 v[34:35], v[26:27], v[48:49] op_sel_hi:[0,1]
	v_pk_mul_f32 v[36:37], v[26:27], v[36:37] op_sel_hi:[0,1]
	v_pk_mul_f32 v[48:49], v[60:61], v[50:51] op_sel_hi:[0,1]
	v_pk_mul_f32 v[38:39], v[60:61], v[38:39] op_sel_hi:[0,1]
	v_pk_mul_f32 v[50:51], v[26:27], v[52:53] op_sel_hi:[0,1]
	v_pk_mul_f32 v[52:53], v[26:27], v[40:41] op_sel_hi:[0,1]
	v_pk_mul_f32 v[54:55], v[60:61], v[54:55] op_sel_hi:[0,1]
	v_pk_mul_f32 v[64:65], v[60:61], v[42:43] op_sel_hi:[0,1]
	v_pk_mul_f32 v[56:57], v[26:27], v[56:57] op_sel_hi:[0,1]
	v_pk_mul_f32 v[66:67], v[26:27], v[44:45] op_sel_hi:[0,1]
	v_pk_mul_f32 v[58:59], v[60:61], v[58:59] op_sel_hi:[0,1]
	v_pk_mul_f32 v[60:61], v[60:61], v[46:47] op_sel_hi:[0,1]
	v_pk_mul_f32 v[28:29], v[2:3], v[28:29]
	v_pk_mul_f32 v[26:27], v[0:1], v[62:63]
	v_pk_mul_f32 v[32:33], v[2:3], v[32:33]
	v_pk_mul_f32 v[30:31], v[0:1], v[30:31]
	v_pk_mul_f32 v[36:37], v[6:7], v[36:37]
	v_pk_mul_f32 v[34:35], v[4:5], v[34:35]
	v_pk_mul_f32 v[40:41], v[6:7], v[38:39]
	v_pk_mul_f32 v[38:39], v[4:5], v[48:49]
	v_pk_mul_f32 v[44:45], v[10:11], v[52:53]
	v_pk_mul_f32 v[42:43], v[8:9], v[50:51]
	v_pk_mul_f32 v[48:49], v[10:11], v[64:65]
	v_pk_mul_f32 v[46:47], v[8:9], v[54:55]
	v_pk_mul_f32 v[52:53], v[14:15], v[66:67]
	v_pk_mul_f32 v[50:51], v[12:13], v[56:57]
	v_pk_mul_f32 v[56:57], v[14:15], v[60:61]
	v_pk_mul_f32 v[54:55], v[12:13], v[58:59]
	global_store_dwordx4 v[22:23], v[26:29], off offset:-4096 nt
	global_store_dwordx4 v[22:23], v[30:33], off nt
	global_store_dwordx4 v[22:23], v[34:37], off offset:-3072 nt
	global_store_dwordx4 v[22:23], v[38:41], off offset:1024 nt
	global_store_dwordx4 v[22:23], v[42:45], off offset:-2048 nt
	global_store_dwordx4 v[22:23], v[46:49], off offset:2048 nt
	global_store_dwordx4 v[22:23], v[50:53], off offset:-1024 nt
	global_store_dwordx4 v[22:23], v[54:57], off offset:3072 nt
	v_lshl_add_u64 v[22:23], v[22:23], 0, s[8:9]

; #define PG8_LAS __attribute__((address_space(3)))
; __global__ void __launch_bounds__(512, 2) hymba_fwd(Params p) {
;     extern __shared__ __attribute__((aligned(16))) unsigned char lds[];
;     cg::grid_group grid = cg::this_grid();
;     unsigned char* ws = p.ws;
;     PG8_LAS unsigned char* glds = (PG8_LAS unsigned char*)lds;
;     const int G = gridDim.x, bx = blockIdx.x;
	.amdhsa_kernel _Z9hymba_fwd6Params
		.amdhsa_group_segment_fixed_size 0
		.amdhsa_private_segment_fixed_size 0
		.amdhsa_kernarg_size 456
		.amdhsa_user_sgpr_count 2
		.amdhsa_user_sgpr_dispatch_ptr 0
		.amdhsa_user_sgpr_queue_ptr 0
		.amdhsa_user_sgpr_kernarg_segment_ptr 1
		.amdhsa_user_sgpr_dispatch_id 0
		.amdhsa_user_sgpr_kernarg_preload_length 0
		.amdhsa_user_sgpr_kernarg_preload_offset 0
		.amdhsa_user_sgpr_private_segment_size 0
		.amdhsa_uses_dynamic_stack 0
		.amdhsa_enable_private_segment 0
		.amdhsa_system_sgpr_workgroup_id_x 1
		.amdhsa_system_sgpr_workgroup_id_y 0
		.amdhsa_system_sgpr_workgroup_id_z 0
		.amdhsa_system_sgpr_workgroup_info 0
		.amdhsa_system_vgpr_workitem_id 2
		.amdhsa_next_free_vgpr 248
		.amdhsa_next_free_sgpr 102
		.amdhsa_accum_offset 248
		.amdhsa_reserve_vcc 1
		.amdhsa_float_round_mode_32 0
		.amdhsa_float_round_mode_16_64 0
		.amdhsa_float_denorm_mode_32 3
		.amdhsa_float_denorm_mode_16_64 3
		.amdhsa_dx10_clamp 1
		.amdhsa_ieee_mode 1
		.amdhsa_fp16_overflow 0
		.amdhsa_tg_split 0
		.amdhsa_exception_fp_ieee_invalid_op 0
		.amdhsa_exception_fp_denorm_src 0
		.amdhsa_exception_fp_ieee_div_zero 0
		.amdhsa_exception_fp_ieee_overflow 0
		.amdhsa_exception_fp_ieee_underflow 0
		.amdhsa_exception_fp_ieee_inexact 0
		.amdhsa_exception_int_div_zero 0
	.end_amdhsa_kernel

; #define PG8_LAS __attribute__((address_space(3)))
; __global__ void __launch_bounds__(512, 2) hymba_fwd(Params p) {
;     extern __shared__ __attribute__((aligned(16))) unsigned char lds[];
;     cg::grid_group grid = cg::this_grid();
;     unsigned char* ws = p.ws;
;     PG8_LAS unsigned char* glds = (PG8_LAS unsigned char*)lds;
;     const int G = gridDim.x, bx = blockIdx.x;
amdhsa.kernels:
  - .agpr_count:     0
    .args:
      - .offset:         0
        .size:           200
        .value_kind:     by_value
      - .offset:         200
        .size:           4
        .value_kind:     hidden_block_count_x
      - .offset:         204
        .size:           4
        .value_kind:     hidden_block_count_y
      - .offset:         208
        .size:           4
        .value_kind:     hidden_block_count_z
      - .offset:         212
        .size:           2
        .value_kind:     hidden_group_size_x
      - .offset:         214
        .size:           2
        .value_kind:     hidden_group_size_y
      - .offset:         216
        .size:           2
        .value_kind:     hidden_group_size_z
      - .offset:         218
        .size:           2
        .value_kind:     hidden_remainder_x
      - .offset:         220
        .size:           2
        .value_kind:     hidden_remainder_y
      - .offset:         222
        .size:           2
        .value_kind:     hidden_remainder_z
      - .offset:         240
        .size:           8
        .value_kind:     hidden_global_offset_x
      - .offset:         248
        .size:           8
        .value_kind:     hidden_global_offset_y
      - .offset:         256
        .size:           8
        .value_kind:     hidden_global_offset_z
      - .offset:         264
        .size:           2
        .value_kind:     hidden_grid_dims
      - .offset:         288
        .size:           8
        .value_kind:     hidden_multigrid_sync_arg
      - .offset:         320
        .size:           4
        .value_kind:     hidden_dynamic_lds_size
    .group_segment_fixed_size: 0
    .kernarg_segment_align: 8
    .kernarg_segment_size: 456
    .language:       OpenCL C
    .language_version:
      - 2
      - 0
    .max_flat_workgroup_size: 512
    .name:           _Z9hymba_fwd6Params
    .private_segment_fixed_size: 0
    .sgpr_count:     108
    .sgpr_spill_count: 55
    .symbol:         _Z9hymba_fwd6Params.kd
    .uniform_work_group_size: 1
    .uses_dynamic_stack: false
    .vgpr_count:     248
    .vgpr_spill_count: 0
    .wavefront_size: 64
